# static priority: leading half (waves 0-3) runs the UP unit epilogue and its first load segment at s_setprio 1, since it has more to do before the next unit's first barrier; otherwise as v71
# baseline (speedup 1.0000x reference)
.LBB0_695:
	s_cmpk_ge_u32 s81, 0x100
	s_cbranch_scc1 .Lupepi_np
	s_setprio 1
